# MW job: the two serialized x4 loads issued together (renamed dest, counted waits)
# baseline (speedup 1.0000x reference)
.LBB0_48:
	v_mov_b32_e32 v32, v208
	s_cmpk_gt_i32 s8, 0x591
	s_mov_b64 s[0:1], -1
	s_cbranch_scc0 .LBB0_95
	s_cmpk_gt_u32 s8, 0xb79
	s_cbranch_scc0 .LBB0_80
	s_cmpk_gt_u32 s8, 0x1179
	s_cbranch_scc0 .LBB0_74
	s_cmpk_gt_u32 s8, 0x12f9
	s_cbranch_scc0 .LBB0_71
	s_add_i32 s5, s8, 0xffffed06
	s_lshl_b32 s0, s5, 5
	s_lshl_b32 s3, s5, 3
	s_and_b32 s4, s0, 0xe0
	s_and_b32 s2, s3, 0xc0
	s_lshl_b32 s0, s4, 2
	v_readlane_b32 s1, v253, 47
	v_ashrrev_i32_e32 v1, 3, v32
	s_add_u32 s0, s1, s0
	v_readlane_b32 s1, v253, 48
	v_lshlrev_b32_e32 v0, 4, v32
	v_add_u32_e32 v2, s2, v1
	s_addc_u32 s1, s1, 0
	v_and_b32_e32 v192, 0x70, v0
	v_ashrrev_i32_e32 v3, 31, v2
	v_lshl_add_u64 v[6:7], s[0:1], 0, v[192:193]
	v_lshlrev_b64 v[2:3], 10, v[2:3]
	v_lshl_add_u64 v[2:3], v[6:7], 0, v[2:3]
	global_load_dwordx4 v[2:5], v[2:3], off
	v_add_u32_e32 v8, 0x100, v32
	v_ashrrev_i32_e32 v9, 3, v8
	v_add_u32_e32 v8, s2, v9
	v_ashrrev_i32_e32 v9, 31, v8
	v_lshlrev_b64 v[10:11], 10, v[8:9]
	v_lshl_add_u64 v[8:9], v[6:7], 0, v[10:11]
	global_load_dwordx4 v[10:13], v[8:9], off
	v_cmp_gt_i32_e32 vcc, 64, v32
	s_waitcnt vmcnt(1)
	ds_write_b128 v0, v[2:5]
	v_add_u32_e32 v2, 0x100, v32
	v_ashrrev_i32_e32 v2, 3, v2
	v_add_u32_e32 v2, s2, v2
	v_ashrrev_i32_e32 v3, 31, v2
	v_lshlrev_b64 v[2:3], 10, v[2:3]
	v_lshl_add_u64 v[2:3], v[6:7], 0, v[2:3]
	s_waitcnt vmcnt(0)
	v_mov_b32_e32 v2, v10
	v_mov_b32_e32 v3, v11
	v_mov_b32_e32 v4, v12
	v_mov_b32_e32 v5, v13
	ds_write_b128 v0, v[2:5] offset:4096
	s_and_saveexec_b64 s[0:1], vcc
	s_cbranch_execz .LBB0_54
	v_cvt_f32_i32_e32 v2, v32
	s_cmp_lt_u32 s5, 32
	s_cselect_b64 vcc, -1, 0
	v_mul_f32_e32 v2, 0x3c800000, v2
	v_cos_f32_e32 v3, v2
	v_sin_f32_e32 v2, v2
	s_nop 0
	v_cndmask_b32_e32 v4, v2, v3, vcc
	v_mad_u64_u32 v[2:3], s[6:7], v32, -12, v[0:1]
	ds_write_b32 v2, v4 offset:8192
